# diff attention loop: s_sleep 6 before the exp/PV block (on top of interleaved packed version)
# baseline (speedup 1.0000x reference)
.LBB0_483:
	s_sleep 6
	v_sub_f32_e32 v0, v150, v0
	v_add3_u32 v203, s5, v133, v130
	ds_read_b128 v[224:227], v203 offset:17408
	ds_read_b128 v[228:231], v203 offset:22016
	ds_read_b128 v[232:235], v203 offset:26624
	ds_read_b128 v[236:239], v203 offset:31232
	ds_read_b128 v[240:243], v203 offset:17440
	ds_read_b128 v[244:247], v203 offset:22048
	ds_read_b128 v[248:251], v203 offset:26656
	ds_read_b128 v[204:207], v203 offset:31264
	v_pk_add_f32 v[82:83], v[82:83], v[0:1] op_sel_hi:[1,0] neg_lo:[0,1] neg_hi:[0,1]
	v_pk_add_f32 v[84:85], v[84:85], v[0:1] op_sel_hi:[1,0] neg_lo:[0,1] neg_hi:[0,1]
	v_exp_f32_e32 v82, v82
	v_exp_f32_e32 v83, v83
	v_pk_add_f32 v[86:87], v[86:87], v[0:1] op_sel_hi:[1,0] neg_lo:[0,1] neg_hi:[0,1]
	v_pk_add_f32 v[88:89], v[88:89], v[0:1] op_sel_hi:[1,0] neg_lo:[0,1] neg_hi:[0,1]
	v_exp_f32_e32 v84, v84
	v_exp_f32_e32 v85, v85
	v_exp_f32_e32 v86, v86
	v_exp_f32_e32 v87, v87
	v_exp_f32_e32 v88, v88
	v_exp_f32_e32 v89, v89
	v_cvt_pk_bf16_f32 v170, v82, v83
	v_cvt_pk_bf16_f32 v171, v84, v85
	v_cvt_pk_bf16_f32 v172, v86, v87
	v_cvt_pk_bf16_f32 v173, v88, v89
	v_pk_add_f32 v[186:187], v[82:83], v[84:85]
	v_pk_add_f32 v[186:187], v[186:187], v[86:87]
	v_pk_add_f32 v[186:187], v[186:187], v[88:89]
	s_setprio 1
	s_waitcnt lgkmcnt(4)
	v_mfma_f32_32x32x16_bf16 v[50:65], v[224:227], v[170:173], v[50:65]
	v_pk_add_f32 v[90:91], v[90:91], v[0:1] op_sel_hi:[1,0] neg_lo:[0,1] neg_hi:[0,1]
	v_pk_add_f32 v[92:93], v[92:93], v[0:1] op_sel_hi:[1,0] neg_lo:[0,1] neg_hi:[0,1]
	v_exp_f32_e32 v90, v90
	v_exp_f32_e32 v91, v91
	v_mfma_f32_32x32x16_bf16 v[34:49], v[228:231], v[170:173], v[34:49]
	v_pk_add_f32 v[94:95], v[94:95], v[0:1] op_sel_hi:[1,0] neg_lo:[0,1] neg_hi:[0,1]
	v_pk_add_f32 v[96:97], v[96:97], v[0:1] op_sel_hi:[1,0] neg_lo:[0,1] neg_hi:[0,1]
	v_exp_f32_e32 v92, v92
	v_exp_f32_e32 v93, v93
	v_mfma_f32_32x32x16_bf16 v[18:33], v[232:235], v[170:173], v[18:33]
	v_exp_f32_e32 v94, v94
	v_exp_f32_e32 v95, v95
	v_exp_f32_e32 v96, v96
	v_exp_f32_e32 v97, v97
	v_cvt_pk_bf16_f32 v174, v90, v91
	v_cvt_pk_bf16_f32 v175, v92, v93
	v_mfma_f32_32x32x16_bf16 v[2:17], v[236:239], v[170:173], v[2:17]
	ds_read_b128 v[224:227], v203 offset:17472
	ds_read_b128 v[228:231], v203 offset:22080
	ds_read_b128 v[232:235], v203 offset:26688
	ds_read_b128 v[236:239], v203 offset:31296
	v_cvt_pk_bf16_f32 v176, v94, v95
	v_cvt_pk_bf16_f32 v177, v96, v97
	v_pk_add_f32 v[186:187], v[186:187], v[90:91]
	v_pk_add_f32 v[186:187], v[186:187], v[92:93]
	v_pk_add_f32 v[186:187], v[186:187], v[94:95]
	v_pk_add_f32 v[186:187], v[186:187], v[96:97]
	s_waitcnt lgkmcnt(4)
	v_mfma_f32_32x32x16_bf16 v[50:65], v[240:243], v[174:177], v[50:65]
	v_pk_add_f32 v[66:67], v[66:67], v[0:1] op_sel_hi:[1,0] neg_lo:[0,1] neg_hi:[0,1]
	v_pk_add_f32 v[68:69], v[68:69], v[0:1] op_sel_hi:[1,0] neg_lo:[0,1] neg_hi:[0,1]
	v_exp_f32_e32 v66, v66
	v_exp_f32_e32 v67, v67
	v_mfma_f32_32x32x16_bf16 v[34:49], v[244:247], v[174:177], v[34:49]
	v_pk_add_f32 v[70:71], v[70:71], v[0:1] op_sel_hi:[1,0] neg_lo:[0,1] neg_hi:[0,1]
	v_pk_add_f32 v[72:73], v[72:73], v[0:1] op_sel_hi:[1,0] neg_lo:[0,1] neg_hi:[0,1]
	v_exp_f32_e32 v68, v68
	v_exp_f32_e32 v69, v69
	v_mfma_f32_32x32x16_bf16 v[18:33], v[248:251], v[174:177], v[18:33]
	v_exp_f32_e32 v70, v70
	v_exp_f32_e32 v71, v71
	v_exp_f32_e32 v72, v72
	v_exp_f32_e32 v73, v73
	v_cvt_pk_bf16_f32 v178, v66, v67
	v_cvt_pk_bf16_f32 v179, v68, v69
	v_mfma_f32_32x32x16_bf16 v[2:17], v[204:207], v[174:177], v[2:17]
	ds_read_b128 v[240:243], v203 offset:17504
	ds_read_b128 v[244:247], v203 offset:22112
	ds_read_b128 v[248:251], v203 offset:26720
	ds_read_b128 v[204:207], v203 offset:31328
	v_cvt_pk_bf16_f32 v180, v70, v71
	v_cvt_pk_bf16_f32 v181, v72, v73
	v_pk_add_f32 v[186:187], v[186:187], v[66:67]
	v_pk_add_f32 v[186:187], v[186:187], v[68:69]
	v_pk_add_f32 v[186:187], v[186:187], v[70:71]
	v_pk_add_f32 v[186:187], v[186:187], v[72:73]
	s_waitcnt lgkmcnt(4)
	v_mfma_f32_32x32x16_bf16 v[50:65], v[224:227], v[178:181], v[50:65]
	v_pk_add_f32 v[74:75], v[74:75], v[0:1] op_sel_hi:[1,0] neg_lo:[0,1] neg_hi:[0,1]
	v_pk_add_f32 v[76:77], v[76:77], v[0:1] op_sel_hi:[1,0] neg_lo:[0,1] neg_hi:[0,1]
	v_exp_f32_e32 v74, v74
	v_exp_f32_e32 v75, v75
	v_mfma_f32_32x32x16_bf16 v[34:49], v[228:231], v[178:181], v[34:49]
	v_pk_add_f32 v[78:79], v[78:79], v[0:1] op_sel_hi:[1,0] neg_lo:[0,1] neg_hi:[0,1]
	v_pk_add_f32 v[80:81], v[80:81], v[0:1] op_sel_hi:[1,0] neg_lo:[0,1] neg_hi:[0,1]
	v_exp_f32_e32 v76, v76
	v_exp_f32_e32 v77, v77
	v_mfma_f32_32x32x16_bf16 v[18:33], v[232:235], v[178:181], v[18:33]
	v_exp_f32_e32 v78, v78
	v_exp_f32_e32 v79, v79
	v_exp_f32_e32 v80, v80
	v_exp_f32_e32 v81, v81
	v_cvt_pk_bf16_f32 v182, v74, v75
	v_cvt_pk_bf16_f32 v183, v76, v77
	v_mfma_f32_32x32x16_bf16 v[2:17], v[236:239], v[178:181], v[2:17]
	v_cvt_pk_bf16_f32 v184, v78, v79
	v_cvt_pk_bf16_f32 v185, v80, v81
	v_pk_add_f32 v[186:187], v[186:187], v[74:75]
	v_pk_add_f32 v[186:187], v[186:187], v[76:77]
	v_pk_add_f32 v[186:187], v[186:187], v[78:79]
	v_pk_add_f32 v[186:187], v[186:187], v[80:81]
	s_waitcnt lgkmcnt(0)
	v_mfma_f32_32x32x16_bf16 v[50:65], v[240:243], v[182:185], v[50:65]
	v_mfma_f32_32x32x16_bf16 v[34:49], v[244:247], v[182:185], v[34:49]
	v_mfma_f32_32x32x16_bf16 v[18:33], v[248:251], v[182:185], v[18:33]
	v_mfma_f32_32x32x16_bf16 v[2:17], v[204:207], v[182:185], v[2:17]
	s_setprio 0
	v_add_f32_e32 v186, v186, v187
	v_add_f32_e32 v131, v131, v186
	s_or_b64 exec, exec, s[64:65]
	s_andn2_b64 vcc, exec, s[62:63]
	s_cbranch_vccnz .LBB0_474
